# grid barrier: non-leader workgroups poll the top-level generation word directly; leader's per-XCD generation atomic dropped (one memory round trip less per barrier)
# speedup vs baseline: 1.0093x; 1.0093x over previous
; __device__ __forceinline__ unsigned xb_ld(unsigned* p)              { return __hip_atomic_load(p, __ATOMIC_RELAXED, __HIP_MEMORY_SCOPE_AGENT); }
; __device__ __forceinline__ unsigned xb_add(unsigned* p, unsigned v) { return __hip_atomic_fetch_add(p, v, __ATOMIC_RELAXED, __HIP_MEMORY_SCOPE_AGENT); }
; #define XB_SPIN(cond, bar) do { unsigned _sp = 0; while (cond) {   \
;     if ((++_sp & 255u) == 0u) { if (xb_ld(&(bar)[XB_TMO])) break; if (_sp > XB_SPIN_CAP) { atomicAdd(&(bar)[XB_TMO], 1u); break; } } } } while (0)
; __device__ __forceinline__ void xcd_barrier(const XcdBarrier& b) {
;     ...
;         const unsigned old = xb_add(&bar[XB_XSUB(b.x)], 1u);
;         const unsigned gen = old / nloc;
;         if (old + 1u == (gen + 1u) * nloc) {
;             __builtin_amdgcn_fence(__ATOMIC_RELEASE, "agent");
;             asm volatile("s_waitcnt vmcnt(0)" ::: "memory");
;             const unsigned og = xb_add(&bar[XB_TOP], 1u);
;             const unsigned tg = og / nx;
;             if (og + 1u == (tg + 1u) * nx) xb_add(&bar[XB_TOPGEN], 1u);
;             else XB_SPIN(xb_ld(&bar[XB_TOPGEN]) == tg, bar);
;             __builtin_amdgcn_fence(__ATOMIC_ACQUIRE, "agent");
;             xb_add(&bar[XB_XGEN(b.x)], 1u);
;             asm volatile("s_waitcnt vmcnt(0)" ::: "memory");
;         } else {
;             XB_SPIN(xb_ld(&bar[XB_XGEN(b.x)]) == gen, bar);
.LBB0_25:
	s_or_b64 exec, exec, s[12:13]
	v_cvt_f32_u32_e32 v5, v3
	s_waitcnt vmcnt(0)
	v_readfirstlane_b32 s0, v4
	v_sub_u32_e32 v4, 0, v3
	v_rcp_iflag_f32_e32 v5, v5
	v_add_u32_e32 v6, s0, v1
	v_mul_f32_e32 v5, 0x4f7ffffe, v5
	v_cvt_u32_f32_e32 v5, v5
	v_mul_lo_u32 v1, v4, v5
	v_mul_hi_u32 v1, v5, v1
	v_add_u32_e32 v1, v5, v1
	v_mul_hi_u32 v1, v6, v1
	v_mul_lo_u32 v4, v1, v3
	v_sub_u32_e32 v4, v6, v4
	v_add_u32_e32 v5, 1, v1
	v_cmp_ge_u32_e32 vcc, v4, v3
	s_nop 1
	v_cndmask_b32_e32 v1, v1, v5, vcc
	v_sub_u32_e32 v5, v4, v3
	v_cndmask_b32_e32 v4, v4, v5, vcc
	v_add_u32_e32 v5, 1, v1
	v_cmp_ge_u32_e32 vcc, v4, v3
	v_add_u32_e32 v4, 1, v6
	s_nop 0
	v_cndmask_b32_e32 v1, v1, v5, vcc
	v_mul_lo_u32 v5, v3, v1
	v_add_u32_e32 v3, v5, v3
	v_cmp_ne_u32_e32 vcc, v4, v3
	s_and_saveexec_b64 s[0:1], vcc
	s_xor_b64 s[8:9], exec, s[0:1]
	s_cbranch_execz .LBB0_39
	s_waitcnt lgkmcnt(0)
	v_mov_b32_e32 v2, 0x3100
	global_load_dword v2, v2, s[90:91] offset:1024 sc1
	s_add_u32 s16, s90, 0x3500
	s_addc_u32 s17, s91, 0
	s_waitcnt vmcnt(0)
	v_cmp_eq_u32_e32 vcc, v2, v1
	s_and_saveexec_b64 s[12:13], vcc
	s_cbranch_execz .LBB0_38
	s_add_u32 s14, s88, 0x2e9d8200
	s_addc_u32 s15, s89, 0
	s_mov_b32 s0, 1
	s_mov_b64 s[18:19], 0
	v_mov_b32_e32 v2, 0
	s_branch .LBB0_29

; __device__ __forceinline__ unsigned xb_add(unsigned* p, unsigned v) { return __hip_atomic_fetch_add(p, v, __ATOMIC_RELAXED, __HIP_MEMORY_SCOPE_AGENT); }
; __device__ __forceinline__ void xcd_barrier(const XcdBarrier& b) {
;     ...
;             __builtin_amdgcn_fence(__ATOMIC_ACQUIRE, "agent");
;             xb_add(&bar[XB_XGEN(b.x)], 1u);
;             asm volatile("s_waitcnt vmcnt(0)" ::: "memory");
.LBB0_56:
	s_or_b64 exec, exec, s[8:9]
	s_mov_b64 s[8:9], exec
	v_mbcnt_lo_u32_b32 v1, s8, 0
	v_mbcnt_hi_u32_b32 v1, s9, v1
	v_cmp_eq_u32_e32 vcc, 0, v1
	s_waitcnt vmcnt(0)
	buffer_inv sc1
	s_and_saveexec_b64 s[12:13], vcc
	s_cbranch_execz .LBB0_58
	s_bcnt1_i32_b64 s0, s[8:9]
	v_mov_b32_e32 v1, 0x2000
	v_mov_b32_e32 v2, s0
.LBB0_58:
	s_or_b64 exec, exec, s[12:13]
	s_waitcnt vmcnt(0)

; __device__ __forceinline__ unsigned xb_add(unsigned* p, unsigned v) { return __hip_atomic_fetch_add(p, v, __ATOMIC_RELAXED, __HIP_MEMORY_SCOPE_AGENT); }
; __device__ __forceinline__ void xcd_barrier(const XcdBarrier& b) {
;     ...
;             __builtin_amdgcn_fence(__ATOMIC_ACQUIRE, "agent");
;             xb_add(&bar[XB_XGEN(b.x)], 1u);
;             asm volatile("s_waitcnt vmcnt(0)" ::: "memory");
.LBB0_309:
	s_or_b64 exec, exec, s[8:9]
	s_mov_b64 s[8:9], exec
	v_mbcnt_lo_u32_b32 v1, s8, 0
	v_mbcnt_hi_u32_b32 v1, s9, v1
	v_cmp_eq_u32_e32 vcc, 0, v1
	s_waitcnt vmcnt(0)
	buffer_inv sc1
	s_and_saveexec_b64 s[12:13], vcc
	s_cbranch_execz .LBB0_311
	s_bcnt1_i32_b64 s0, s[8:9]
	v_mov_b32_e32 v1, 0x2000
	v_mov_b32_e32 v2, s0
.LBB0_311:
	s_or_b64 exec, exec, s[12:13]
	s_waitcnt vmcnt(0)

; __device__ __forceinline__ unsigned xb_add(unsigned* p, unsigned v) { return __hip_atomic_fetch_add(p, v, __ATOMIC_RELAXED, __HIP_MEMORY_SCOPE_AGENT); }
; __device__ __forceinline__ void xcd_barrier(const XcdBarrier& b) {
;     ...
;             __builtin_amdgcn_fence(__ATOMIC_ACQUIRE, "agent");
;             xb_add(&bar[XB_XGEN(b.x)], 1u);
;             asm volatile("s_waitcnt vmcnt(0)" ::: "memory");
.LBB0_370:
	s_or_b64 exec, exec, s[8:9]
	s_mov_b64 s[8:9], exec
	v_mbcnt_lo_u32_b32 v1, s8, 0
	v_mbcnt_hi_u32_b32 v1, s9, v1
	v_cmp_eq_u32_e32 vcc, 0, v1
	s_waitcnt vmcnt(0)
	buffer_inv sc1
	s_and_saveexec_b64 s[12:13], vcc
	s_cbranch_execz .LBB0_372
	s_bcnt1_i32_b64 s0, s[8:9]
	v_mov_b32_e32 v1, 0x2000
	v_mov_b32_e32 v2, s0
.LBB0_372:
	s_or_b64 exec, exec, s[12:13]
	s_waitcnt vmcnt(0)

; __device__ __forceinline__ unsigned xb_add(unsigned* p, unsigned v) { return __hip_atomic_fetch_add(p, v, __ATOMIC_RELAXED, __HIP_MEMORY_SCOPE_AGENT); }
; __device__ __forceinline__ void xcd_barrier(const XcdBarrier& b) {
;     ...
;             __builtin_amdgcn_fence(__ATOMIC_ACQUIRE, "agent");
;             xb_add(&bar[XB_XGEN(b.x)], 1u);
;             asm volatile("s_waitcnt vmcnt(0)" ::: "memory");
.LBB0_487:
	s_or_b64 exec, exec, s[8:9]
	s_mov_b64 s[8:9], exec
	v_mbcnt_lo_u32_b32 v1, s8, 0
	v_mbcnt_hi_u32_b32 v1, s9, v1
	v_cmp_eq_u32_e32 vcc, 0, v1
	s_waitcnt vmcnt(0)
	buffer_inv sc1
	s_and_saveexec_b64 s[12:13], vcc
	s_cbranch_execz .LBB0_489
	s_bcnt1_i32_b64 s0, s[8:9]
	v_mov_b32_e32 v1, 0x2000
	v_mov_b32_e32 v2, s0
.LBB0_489:
	s_or_b64 exec, exec, s[12:13]
	s_waitcnt vmcnt(0)

; __device__ __forceinline__ unsigned xb_add(unsigned* p, unsigned v) { return __hip_atomic_fetch_add(p, v, __ATOMIC_RELAXED, __HIP_MEMORY_SCOPE_AGENT); }
; __device__ __forceinline__ void xcd_barrier(const XcdBarrier& b) {
;     ...
;             __builtin_amdgcn_fence(__ATOMIC_ACQUIRE, "agent");
;             xb_add(&bar[XB_XGEN(b.x)], 1u);
;             asm volatile("s_waitcnt vmcnt(0)" ::: "memory");
.LBB0_559:
	s_or_b64 exec, exec, s[8:9]
	s_mov_b64 s[8:9], exec
	v_mbcnt_lo_u32_b32 v1, s8, 0
	v_mbcnt_hi_u32_b32 v1, s9, v1
	v_cmp_eq_u32_e32 vcc, 0, v1
	s_waitcnt vmcnt(0)
	buffer_inv sc1
	s_and_saveexec_b64 s[12:13], vcc
	s_cbranch_execz .LBB0_561
	s_bcnt1_i32_b64 s0, s[8:9]
	v_mov_b32_e32 v1, 0x2000
	v_mov_b32_e32 v2, s0
.LBB0_561:
	s_or_b64 exec, exec, s[12:13]
	s_waitcnt vmcnt(0)

; __device__ __forceinline__ unsigned xb_add(unsigned* p, unsigned v) { return __hip_atomic_fetch_add(p, v, __ATOMIC_RELAXED, __HIP_MEMORY_SCOPE_AGENT); }
; __device__ __forceinline__ void xcd_barrier(const XcdBarrier& b) {
;     ...
;             __builtin_amdgcn_fence(__ATOMIC_ACQUIRE, "agent");
;             xb_add(&bar[XB_XGEN(b.x)], 1u);
;             asm volatile("s_waitcnt vmcnt(0)" ::: "memory");
.LBB0_636:
	s_or_b64 exec, exec, s[8:9]
	s_mov_b64 s[8:9], exec
	v_mbcnt_lo_u32_b32 v1, s8, 0
	v_mbcnt_hi_u32_b32 v1, s9, v1
	v_cmp_eq_u32_e32 vcc, 0, v1
	s_waitcnt vmcnt(0)
	buffer_inv sc1
	s_and_saveexec_b64 s[12:13], vcc
	s_cbranch_execz .LBB0_638
	s_bcnt1_i32_b64 s0, s[8:9]
	v_mov_b32_e32 v1, 0x2000
	v_mov_b32_e32 v2, s0
.LBB0_638:
	s_or_b64 exec, exec, s[12:13]
	s_waitcnt vmcnt(0)

; __device__ __forceinline__ unsigned xb_add(unsigned* p, unsigned v) { return __hip_atomic_fetch_add(p, v, __ATOMIC_RELAXED, __HIP_MEMORY_SCOPE_AGENT); }
; __device__ __forceinline__ void xcd_barrier(const XcdBarrier& b) {
;     ...
;             __builtin_amdgcn_fence(__ATOMIC_ACQUIRE, "agent");
;             xb_add(&bar[XB_XGEN(b.x)], 1u);
;             asm volatile("s_waitcnt vmcnt(0)" ::: "memory");
.LBB0_708:
	s_or_b64 exec, exec, s[8:9]
	s_mov_b64 s[8:9], exec
	v_mbcnt_lo_u32_b32 v1, s8, 0
	v_mbcnt_hi_u32_b32 v1, s9, v1
	v_cmp_eq_u32_e32 vcc, 0, v1
	s_waitcnt vmcnt(0)
	buffer_inv sc1
	s_and_saveexec_b64 s[12:13], vcc
	s_cbranch_execz .LBB0_710
	s_bcnt1_i32_b64 s0, s[8:9]
	v_mov_b32_e32 v1, 0x2000
	v_mov_b32_e32 v2, s0
.LBB0_710:
	s_or_b64 exec, exec, s[12:13]
	s_waitcnt vmcnt(0)

; __device__ __forceinline__ unsigned xb_add(unsigned* p, unsigned v) { return __hip_atomic_fetch_add(p, v, __ATOMIC_RELAXED, __HIP_MEMORY_SCOPE_AGENT); }
; __device__ __forceinline__ void xcd_barrier(const XcdBarrier& b) {
;     ...
;             __builtin_amdgcn_fence(__ATOMIC_ACQUIRE, "agent");
;             xb_add(&bar[XB_XGEN(b.x)], 1u);
;             asm volatile("s_waitcnt vmcnt(0)" ::: "memory");
.LBB0_817:
	s_or_b64 exec, exec, s[8:9]
	s_mov_b64 s[8:9], exec
	v_mbcnt_lo_u32_b32 v1, s8, 0
	v_mbcnt_hi_u32_b32 v1, s9, v1
	v_cmp_eq_u32_e32 vcc, 0, v1
	s_waitcnt vmcnt(0)
	buffer_inv sc1
	s_and_saveexec_b64 s[12:13], vcc
	s_cbranch_execz .LBB0_819
	s_bcnt1_i32_b64 s0, s[8:9]
	v_mov_b32_e32 v1, 0x2000
	v_mov_b32_e32 v2, s0
.LBB0_819:
	s_or_b64 exec, exec, s[12:13]
	s_waitcnt vmcnt(0)

; __device__ __forceinline__ unsigned xb_add(unsigned* p, unsigned v) { return __hip_atomic_fetch_add(p, v, __ATOMIC_RELAXED, __HIP_MEMORY_SCOPE_AGENT); }
; __device__ __forceinline__ void xcd_barrier(const XcdBarrier& b) {
;     ...
;             __builtin_amdgcn_fence(__ATOMIC_ACQUIRE, "agent");
;             xb_add(&bar[XB_XGEN(b.x)], 1u);
;             asm volatile("s_waitcnt vmcnt(0)" ::: "memory");
.LBB0_930:
	s_or_b64 exec, exec, s[8:9]
	s_mov_b64 s[8:9], exec
	v_mbcnt_lo_u32_b32 v1, s8, 0
	v_mbcnt_hi_u32_b32 v1, s9, v1
	v_cmp_eq_u32_e32 vcc, 0, v1
	s_waitcnt vmcnt(0)
	buffer_inv sc1
	s_and_saveexec_b64 s[12:13], vcc
	s_cbranch_execz .LBB0_932
	s_bcnt1_i32_b64 s0, s[8:9]
	v_mov_b32_e32 v1, 0x2000
	v_mov_b32_e32 v2, s0
.LBB0_932:
	s_or_b64 exec, exec, s[12:13]
	s_waitcnt vmcnt(0)

; __device__ __forceinline__ unsigned xb_add(unsigned* p, unsigned v) { return __hip_atomic_fetch_add(p, v, __ATOMIC_RELAXED, __HIP_MEMORY_SCOPE_AGENT); }
; __device__ __forceinline__ void xcd_barrier(const XcdBarrier& b) {
;     ...
;             __builtin_amdgcn_fence(__ATOMIC_ACQUIRE, "agent");
;             xb_add(&bar[XB_XGEN(b.x)], 1u);
;             asm volatile("s_waitcnt vmcnt(0)" ::: "memory");
.LBB0_1013:
	s_or_b64 exec, exec, s[8:9]
	s_mov_b64 s[8:9], exec
	v_mbcnt_lo_u32_b32 v1, s8, 0
	v_mbcnt_hi_u32_b32 v1, s9, v1
	v_cmp_eq_u32_e32 vcc, 0, v1
	s_waitcnt vmcnt(0)
	buffer_inv sc1
	s_and_saveexec_b64 s[12:13], vcc
	s_cbranch_execz .LBB0_1015
	s_bcnt1_i32_b64 s0, s[8:9]
	v_mov_b32_e32 v1, 0x2000
	v_mov_b32_e32 v2, s0
.LBB0_1015:
	s_or_b64 exec, exec, s[12:13]
	s_waitcnt vmcnt(0)

; __device__ __forceinline__ unsigned xb_add(unsigned* p, unsigned v) { return __hip_atomic_fetch_add(p, v, __ATOMIC_RELAXED, __HIP_MEMORY_SCOPE_AGENT); }
; __device__ __forceinline__ void xcd_barrier(const XcdBarrier& b) {
;     ...
;             __builtin_amdgcn_fence(__ATOMIC_ACQUIRE, "agent");
;             xb_add(&bar[XB_XGEN(b.x)], 1u);
;             asm volatile("s_waitcnt vmcnt(0)" ::: "memory");
.LBB0_1074:
	s_or_b64 exec, exec, s[8:9]
	s_mov_b64 s[8:9], exec
	v_mbcnt_lo_u32_b32 v1, s8, 0
	v_mbcnt_hi_u32_b32 v1, s9, v1
	v_cmp_eq_u32_e32 vcc, 0, v1
	s_waitcnt vmcnt(0)
	buffer_inv sc1
	s_and_saveexec_b64 s[12:13], vcc
	s_cbranch_execz .LBB0_1076
	s_bcnt1_i32_b64 s0, s[8:9]
	v_mov_b32_e32 v1, 0x2000
	v_mov_b32_e32 v2, s0
.LBB0_1076:
	s_or_b64 exec, exec, s[12:13]
	s_waitcnt vmcnt(0)

; __device__ __forceinline__ unsigned xb_add(unsigned* p, unsigned v) { return __hip_atomic_fetch_add(p, v, __ATOMIC_RELAXED, __HIP_MEMORY_SCOPE_AGENT); }
; __device__ __forceinline__ void xcd_barrier(const XcdBarrier& b) {
;     ...
;             __builtin_amdgcn_fence(__ATOMIC_ACQUIRE, "agent");
;             xb_add(&bar[XB_XGEN(b.x)], 1u);
;             asm volatile("s_waitcnt vmcnt(0)" ::: "memory");
.LBB0_1165:
	s_or_b64 exec, exec, s[8:9]
	s_mov_b64 s[8:9], exec
	v_mbcnt_lo_u32_b32 v1, s8, 0
	v_mbcnt_hi_u32_b32 v1, s9, v1
	v_cmp_eq_u32_e32 vcc, 0, v1
	s_waitcnt vmcnt(0)
	buffer_inv sc1
	s_and_saveexec_b64 s[12:13], vcc
	s_cbranch_execz .LBB0_1167
	s_bcnt1_i32_b64 s0, s[8:9]
	v_mov_b32_e32 v1, 0x2000
	v_mov_b32_e32 v2, s0
.LBB0_1167:
	s_or_b64 exec, exec, s[12:13]
	s_waitcnt vmcnt(0)

; __device__ __forceinline__ unsigned xb_add(unsigned* p, unsigned v) { return __hip_atomic_fetch_add(p, v, __ATOMIC_RELAXED, __HIP_MEMORY_SCOPE_AGENT); }
; __device__ __forceinline__ void xcd_barrier(const XcdBarrier& b) {
;     ...
;             __builtin_amdgcn_fence(__ATOMIC_ACQUIRE, "agent");
;             xb_add(&bar[XB_XGEN(b.x)], 1u);
;             asm volatile("s_waitcnt vmcnt(0)" ::: "memory");
.LBB0_1237:
	s_or_b64 exec, exec, s[8:9]
	s_mov_b64 s[8:9], exec
	v_mbcnt_lo_u32_b32 v1, s8, 0
	v_mbcnt_hi_u32_b32 v1, s9, v1
	v_cmp_eq_u32_e32 vcc, 0, v1
	s_waitcnt vmcnt(0)
	buffer_inv sc1
	s_and_saveexec_b64 s[12:13], vcc
	s_cbranch_execz .LBB0_1239
	s_bcnt1_i32_b64 s0, s[8:9]
	v_mov_b32_e32 v1, 0x2000
	v_mov_b32_e32 v2, s0
.LBB0_1239:
	s_or_b64 exec, exec, s[12:13]
	s_waitcnt vmcnt(0)

; __device__ __forceinline__ unsigned xb_add(unsigned* p, unsigned v) { return __hip_atomic_fetch_add(p, v, __ATOMIC_RELAXED, __HIP_MEMORY_SCOPE_AGENT); }
; __device__ __forceinline__ void xcd_barrier(const XcdBarrier& b) {
;     ...
;             __builtin_amdgcn_fence(__ATOMIC_ACQUIRE, "agent");
;             xb_add(&bar[XB_XGEN(b.x)], 1u);
;             asm volatile("s_waitcnt vmcnt(0)" ::: "memory");
.LBB0_1306:
	s_or_b64 exec, exec, s[8:9]
	s_mov_b64 s[8:9], exec
	v_mbcnt_lo_u32_b32 v1, s8, 0
	v_mbcnt_hi_u32_b32 v1, s9, v1
	v_cmp_eq_u32_e32 vcc, 0, v1
	s_waitcnt vmcnt(0)
	buffer_inv sc1
	s_and_saveexec_b64 s[12:13], vcc
	s_cbranch_execz .LBB0_1308
	s_bcnt1_i32_b64 s0, s[8:9]
	v_mov_b32_e32 v1, 0x2000
	v_mov_b32_e32 v2, s0
.LBB0_1308:
	s_or_b64 exec, exec, s[12:13]
	s_waitcnt vmcnt(0)

; __device__ __forceinline__ unsigned xb_add(unsigned* p, unsigned v) { return __hip_atomic_fetch_add(p, v, __ATOMIC_RELAXED, __HIP_MEMORY_SCOPE_AGENT); }
; __device__ __forceinline__ void xcd_barrier(const XcdBarrier& b) {
;     ...
;             __builtin_amdgcn_fence(__ATOMIC_ACQUIRE, "agent");
;             xb_add(&bar[XB_XGEN(b.x)], 1u);
;             asm volatile("s_waitcnt vmcnt(0)" ::: "memory");
.LBB0_1378:
	s_or_b64 exec, exec, s[8:9]
	s_mov_b64 s[8:9], exec
	v_mbcnt_lo_u32_b32 v1, s8, 0
	v_mbcnt_hi_u32_b32 v1, s9, v1
	v_cmp_eq_u32_e32 vcc, 0, v1
	s_waitcnt vmcnt(0)
	buffer_inv sc1
	s_and_saveexec_b64 s[12:13], vcc
	s_cbranch_execz .LBB0_1380
	s_bcnt1_i32_b64 s0, s[8:9]
	v_mov_b32_e32 v1, 0x2000
	v_mov_b32_e32 v2, s0
.LBB0_1380:
	s_or_b64 exec, exec, s[12:13]
	s_waitcnt vmcnt(0)

; __device__ __forceinline__ unsigned xb_add(unsigned* p, unsigned v) { return __hip_atomic_fetch_add(p, v, __ATOMIC_RELAXED, __HIP_MEMORY_SCOPE_AGENT); }
; __device__ __forceinline__ void xcd_barrier(const XcdBarrier& b) {
;     ...
;             __builtin_amdgcn_fence(__ATOMIC_ACQUIRE, "agent");
;             xb_add(&bar[XB_XGEN(b.x)], 1u);
;             asm volatile("s_waitcnt vmcnt(0)" ::: "memory");
.LBB0_1471:
	s_or_b64 exec, exec, s[8:9]
	s_mov_b64 s[8:9], exec
	v_mbcnt_lo_u32_b32 v1, s8, 0
	v_mbcnt_hi_u32_b32 v1, s9, v1
	v_cmp_eq_u32_e32 vcc, 0, v1
	s_waitcnt vmcnt(0)
	buffer_inv sc1
	s_and_saveexec_b64 s[12:13], vcc
	s_cbranch_execz .LBB0_1473
	s_bcnt1_i32_b64 s0, s[8:9]
	v_mov_b32_e32 v1, 0x2000
	v_mov_b32_e32 v2, s0
.LBB0_1473:
	s_or_b64 exec, exec, s[12:13]
	s_waitcnt vmcnt(0)

; __device__ __forceinline__ unsigned xb_add(unsigned* p, unsigned v) { return __hip_atomic_fetch_add(p, v, __ATOMIC_RELAXED, __HIP_MEMORY_SCOPE_AGENT); }
; __device__ __forceinline__ void xcd_barrier(const XcdBarrier& b) {
;     ...
;             __builtin_amdgcn_fence(__ATOMIC_ACQUIRE, "agent");
;             xb_add(&bar[XB_XGEN(b.x)], 1u);
;             asm volatile("s_waitcnt vmcnt(0)" ::: "memory");
.LBB0_1574:
	s_or_b64 exec, exec, s[8:9]
	s_mov_b64 s[8:9], exec
	v_mbcnt_lo_u32_b32 v1, s8, 0
	v_mbcnt_hi_u32_b32 v1, s9, v1
	v_cmp_eq_u32_e32 vcc, 0, v1
	s_waitcnt vmcnt(0)
	buffer_inv sc1
	s_and_saveexec_b64 s[12:13], vcc
	s_cbranch_execz .LBB0_1576
	s_bcnt1_i32_b64 s0, s[8:9]
	v_mov_b32_e32 v1, 0x2000
	v_mov_b32_e32 v2, s0
.LBB0_1576:
	s_or_b64 exec, exec, s[12:13]
	s_waitcnt vmcnt(0)

; __device__ __forceinline__ unsigned xb_add(unsigned* p, unsigned v) { return __hip_atomic_fetch_add(p, v, __ATOMIC_RELAXED, __HIP_MEMORY_SCOPE_AGENT); }
; __device__ __forceinline__ void xcd_barrier(const XcdBarrier& b) {
;     ...
;             __builtin_amdgcn_fence(__ATOMIC_ACQUIRE, "agent");
;             xb_add(&bar[XB_XGEN(b.x)], 1u);
;             asm volatile("s_waitcnt vmcnt(0)" ::: "memory");
.LBB0_1649:
	s_or_b64 exec, exec, s[8:9]
	s_mov_b64 s[8:9], exec
	v_mbcnt_lo_u32_b32 v1, s8, 0
	v_mbcnt_hi_u32_b32 v1, s9, v1
	v_cmp_eq_u32_e32 vcc, 0, v1
	s_waitcnt vmcnt(0)
	buffer_inv sc1
	s_and_saveexec_b64 s[10:11], vcc
	s_cbranch_execz .LBB0_1651
	s_bcnt1_i32_b64 s0, s[8:9]
	v_mov_b32_e32 v1, 0x2000
	v_mov_b32_e32 v2, s0
.LBB0_1651:
	s_or_b64 exec, exec, s[10:11]
	s_waitcnt vmcnt(0)
